# combined: packed multiplies in hn block, 8 table regions, batched residual-GEMM epilogue loads, gMLP bias loads hoisted out of the store ladder
# speedup vs baseline: 1.0078x; 1.0078x over previous
; __device__ __forceinline__ unsigned cvt_pk_bf16(float lo, float hi) { unsigned r; asm volatile("v_cvt_pk_bf16_f32 %0, %1, %2" : "=v"(r) : "v"(lo), "v"(hi)); return r; }
; __device__ __forceinline__ float bflo(unsigned w) { return __uint_as_float(w << 16); }
; __device__ __forceinline__ float bfhi(unsigned w) { return __uint_as_float(w & 0xffff0000u); }
; __device__ void ph_peer(const float* __restrict__ SC, const bf16_t* __restrict__ H  , const float* __restrict__ gffn, const unsigned char* __restrict__ U, const unsigned char* __restrict__ V, float* X, const float* __restrict__ fgain) {
;     ...
;         {   const u32x4* hp = (const u32x4*)(H + (size_t)tok * 1024 + 64 * sub);
; #pragma unroll
;             for (int q = 0; q < 8; ++q) { const u32x4 w = hp[q];
;                 const float4 ga = *(const float4*)(gffn + 64 * sub + q * 8), gb = *(const float4*)(gffn + 64 * sub + q * 8 + 4);
;                 hf2[q * 4 + 0] = cvt_pk_bf16(bflo(w.x) * rstd * ga.x, bfhi(w.x) * rstd * ga.y);
;                 hf2[q * 4 + 1] = cvt_pk_bf16(bflo(w.y) * rstd * ga.z, bfhi(w.y) * rstd * ga.w);
;                 hf2[q * 4 + 2] = cvt_pk_bf16(bflo(w.z) * rstd * gb.x, bfhi(w.z) * rstd * gb.y);
;                 hf2[q * 4 + 3] = cvt_pk_bf16(bflo(w.w) * rstd * gb.z, bfhi(w.w) * rstd * gb.w); } }
.LBB0_230:
	s_waitcnt vmcnt(0) lgkmcnt(0)
	v_lshlrev_b32_e32 v2, 16, v180
	v_and_b32_e32 v3, 0xffff0000, v180
	v_lshlrev_b32_e32 v4, 16, v181
	v_and_b32_e32 v5, 0xffff0000, v181
	v_pk_mul_f32 v[2:3], v[2:3], v[12:13] op_sel_hi:[1,0]
	v_pk_mul_f32 v[4:5], v[4:5], v[12:13] op_sel_hi:[1,0]
	v_pk_mul_f32 v[2:3], v[2:3], v[64:65]
	v_pk_mul_f32 v[4:5], v[4:5], v[66:67]
	v_cvt_pk_bf16_f32 v95, v2, v3
	v_cvt_pk_bf16_f32 v159, v4, v5
	v_lshlrev_b32_e32 v2, 16, v182
	v_and_b32_e32 v3, 0xffff0000, v182
	v_lshlrev_b32_e32 v4, 16, v183
	v_and_b32_e32 v5, 0xffff0000, v183
	v_pk_mul_f32 v[2:3], v[2:3], v[12:13] op_sel_hi:[1,0]
	v_pk_mul_f32 v[4:5], v[4:5], v[12:13] op_sel_hi:[1,0]
	v_pk_mul_f32 v[2:3], v[2:3], v[68:69]
	v_pk_mul_f32 v[4:5], v[4:5], v[70:71]
	v_cvt_pk_bf16_f32 v160, v2, v3
	v_cvt_pk_bf16_f32 v161, v4, v5
	v_lshlrev_b32_e32 v2, 16, v184
	v_and_b32_e32 v3, 0xffff0000, v184
	v_lshlrev_b32_e32 v4, 16, v185
	v_and_b32_e32 v5, 0xffff0000, v185
	v_pk_mul_f32 v[2:3], v[2:3], v[12:13] op_sel_hi:[1,0]
	v_pk_mul_f32 v[4:5], v[4:5], v[12:13] op_sel_hi:[1,0]
	v_pk_mul_f32 v[2:3], v[2:3], v[32:33]
	v_pk_mul_f32 v[4:5], v[4:5], v[34:35]
	v_cvt_pk_bf16_f32 v180, v2, v3
	v_cvt_pk_bf16_f32 v181, v4, v5
	v_lshlrev_b32_e32 v2, 16, v186
	v_and_b32_e32 v3, 0xffff0000, v186
	v_lshlrev_b32_e32 v4, 16, v187
	v_and_b32_e32 v5, 0xffff0000, v187
	v_pk_mul_f32 v[2:3], v[2:3], v[12:13] op_sel_hi:[1,0]
	v_pk_mul_f32 v[4:5], v[4:5], v[12:13] op_sel_hi:[1,0]
	v_pk_mul_f32 v[2:3], v[2:3], v[36:37]
	v_pk_mul_f32 v[4:5], v[4:5], v[38:39]
	v_cvt_pk_bf16_f32 v182, v2, v3
	v_cvt_pk_bf16_f32 v183, v4, v5
	v_lshlrev_b32_e32 v2, 16, v188
	v_and_b32_e32 v3, 0xffff0000, v188
	v_lshlrev_b32_e32 v4, 16, v189
	v_and_b32_e32 v5, 0xffff0000, v189
	v_pk_mul_f32 v[2:3], v[2:3], v[12:13] op_sel_hi:[1,0]
	v_pk_mul_f32 v[4:5], v[4:5], v[12:13] op_sel_hi:[1,0]
	v_pk_mul_f32 v[2:3], v[2:3], v[40:41]
	v_pk_mul_f32 v[4:5], v[4:5], v[42:43]
	v_cvt_pk_bf16_f32 v184, v2, v3
	v_cvt_pk_bf16_f32 v185, v4, v5
	v_lshlrev_b32_e32 v2, 16, v190
	v_and_b32_e32 v3, 0xffff0000, v190
	v_lshlrev_b32_e32 v4, 16, v191
	v_and_b32_e32 v5, 0xffff0000, v191
	v_pk_mul_f32 v[2:3], v[2:3], v[12:13] op_sel_hi:[1,0]
	v_pk_mul_f32 v[4:5], v[4:5], v[12:13] op_sel_hi:[1,0]
	v_pk_mul_f32 v[2:3], v[2:3], v[44:45]
	v_pk_mul_f32 v[4:5], v[4:5], v[46:47]
	v_cvt_pk_bf16_f32 v186, v2, v3
	v_cvt_pk_bf16_f32 v187, v4, v5
	v_lshlrev_b32_e32 v2, 16, v192
	v_and_b32_e32 v3, 0xffff0000, v192
	v_lshlrev_b32_e32 v4, 16, v193
	v_and_b32_e32 v5, 0xffff0000, v193
	v_pk_mul_f32 v[2:3], v[2:3], v[12:13] op_sel_hi:[1,0]
	v_pk_mul_f32 v[4:5], v[4:5], v[12:13] op_sel_hi:[1,0]
	v_pk_mul_f32 v[2:3], v[2:3], v[48:49]
	v_pk_mul_f32 v[4:5], v[4:5], v[50:51]
	v_cvt_pk_bf16_f32 v188, v2, v3
	v_cvt_pk_bf16_f32 v189, v4, v5
	v_lshlrev_b32_e32 v2, 16, v194
	v_and_b32_e32 v3, 0xffff0000, v194
	v_lshlrev_b32_e32 v4, 16, v195
	v_and_b32_e32 v5, 0xffff0000, v195
	v_pk_mul_f32 v[2:3], v[2:3], v[12:13] op_sel_hi:[1,0]
	v_pk_mul_f32 v[4:5], v[4:5], v[12:13] op_sel_hi:[1,0]
	v_pk_mul_f32 v[2:3], v[2:3], v[52:53]
	v_pk_mul_f32 v[4:5], v[4:5], v[54:55]
	v_cvt_pk_bf16_f32 v190, v2, v3
	v_cvt_pk_bf16_f32 v191, v4, v5
	v_lshlrev_b32_e32 v2, 16, v196
	v_and_b32_e32 v3, 0xffff0000, v196
	v_lshlrev_b32_e32 v4, 16, v197
	v_and_b32_e32 v5, 0xffff0000, v197
	v_pk_mul_f32 v[2:3], v[2:3], v[12:13] op_sel_hi:[1,0]
	v_pk_mul_f32 v[4:5], v[4:5], v[12:13] op_sel_hi:[1,0]
	v_pk_mul_f32 v[2:3], v[2:3], v[56:57]
	v_pk_mul_f32 v[4:5], v[4:5], v[58:59]
	v_cvt_pk_bf16_f32 v192, v2, v3
	v_cvt_pk_bf16_f32 v193, v4, v5
	v_lshlrev_b32_e32 v2, 16, v198
	v_and_b32_e32 v3, 0xffff0000, v198
	v_lshlrev_b32_e32 v4, 16, v199
	v_and_b32_e32 v5, 0xffff0000, v199
	v_pk_mul_f32 v[2:3], v[2:3], v[12:13] op_sel_hi:[1,0]
	v_pk_mul_f32 v[4:5], v[4:5], v[12:13] op_sel_hi:[1,0]
	v_pk_mul_f32 v[2:3], v[2:3], v[60:61]
	v_pk_mul_f32 v[4:5], v[4:5], v[62:63]
	v_cvt_pk_bf16_f32 v194, v2, v3
	v_cvt_pk_bf16_f32 v195, v4, v5
	v_lshlrev_b32_e32 v2, 16, v200
	v_and_b32_e32 v3, 0xffff0000, v200
	v_lshlrev_b32_e32 v4, 16, v201
	v_and_b32_e32 v5, 0xffff0000, v201
	v_pk_mul_f32 v[2:3], v[2:3], v[12:13] op_sel_hi:[1,0]
	v_pk_mul_f32 v[4:5], v[4:5], v[12:13] op_sel_hi:[1,0]
	v_pk_mul_f32 v[2:3], v[2:3], v[98:99]
	v_pk_mul_f32 v[4:5], v[4:5], v[100:101]
	v_cvt_pk_bf16_f32 v196, v2, v3
	v_cvt_pk_bf16_f32 v197, v4, v5
	v_lshlrev_b32_e32 v2, 16, v202
	v_and_b32_e32 v3, 0xffff0000, v202
	v_lshlrev_b32_e32 v4, 16, v203
	v_and_b32_e32 v5, 0xffff0000, v203
	v_pk_mul_f32 v[2:3], v[2:3], v[12:13] op_sel_hi:[1,0]
	v_pk_mul_f32 v[4:5], v[4:5], v[12:13] op_sel_hi:[1,0]
	v_pk_mul_f32 v[2:3], v[2:3], v[102:103]
	v_pk_mul_f32 v[4:5], v[4:5], v[104:105]
	v_cvt_pk_bf16_f32 v198, v2, v3
	v_cvt_pk_bf16_f32 v199, v4, v5
	v_lshlrev_b32_e32 v2, 16, v204
	v_and_b32_e32 v3, 0xffff0000, v204
	v_lshlrev_b32_e32 v4, 16, v205
	v_and_b32_e32 v5, 0xffff0000, v205
	v_pk_mul_f32 v[2:3], v[2:3], v[12:13] op_sel_hi:[1,0]
	v_pk_mul_f32 v[4:5], v[4:5], v[12:13] op_sel_hi:[1,0]
	v_pk_mul_f32 v[2:3], v[2:3], v[106:107]
	v_pk_mul_f32 v[4:5], v[4:5], v[108:109]
	v_cvt_pk_bf16_f32 v200, v2, v3
	v_cvt_pk_bf16_f32 v201, v4, v5
	v_lshlrev_b32_e32 v2, 16, v206
	v_and_b32_e32 v3, 0xffff0000, v206
	v_lshlrev_b32_e32 v4, 16, v207
	v_and_b32_e32 v5, 0xffff0000, v207
	v_pk_mul_f32 v[2:3], v[2:3], v[12:13] op_sel_hi:[1,0]
	v_pk_mul_f32 v[4:5], v[4:5], v[12:13] op_sel_hi:[1,0]
	v_pk_mul_f32 v[2:3], v[2:3], v[110:111]
	v_pk_mul_f32 v[4:5], v[4:5], v[112:113]
	v_cvt_pk_bf16_f32 v202, v2, v3
	v_cvt_pk_bf16_f32 v203, v4, v5
	v_lshlrev_b32_e32 v2, 16, v208
	v_and_b32_e32 v3, 0xffff0000, v208
	v_lshlrev_b32_e32 v4, 16, v209
	v_and_b32_e32 v5, 0xffff0000, v209
; __device__ __forceinline__ unsigned cvt_pk_bf16(float lo, float hi) { unsigned r; asm volatile("v_cvt_pk_bf16_f32 %0, %1, %2" : "=v"(r) : "v"(lo), "v"(hi)); return r; }
; __device__ __forceinline__ float bflo(unsigned w) { return __uint_as_float(w << 16); }
; __device__ __forceinline__ float bfhi(unsigned w) { return __uint_as_float(w & 0xffff0000u); }
; __device__ void ph_peer(const float* __restrict__ SC, const bf16_t* __restrict__ H  , const float* __restrict__ gffn, const unsigned char* __restrict__ U, const unsigned char* __restrict__ V, float* X, const float* __restrict__ fgain) {
;     ...
;         {   const u32x4* hp0 = (const u32x4*)(H + (size_t)tok * 1024); float ss = 0.f;
; #pragma unroll
;             for (int s4 = 0; s4 < 2; ++s4) { const u32x4 w = hp0[s4 * 64 + lane]; const unsigned ww[4] = {w.x, w.y, w.z, w.w};
; #pragma unroll
;                 for (int e4 = 0; e4 < 4; ++e4) { const float lo = bflo(ww[e4]), hi = bfhi(ww[e4]); ss += lo * lo + hi * hi; } }
;             ss = wave_sum(ss); rstd = rsqrtf(ss * (1.0f / 1024.0f) + 1e-6f); }
;     ...
;         {   const u32x4* hp = (const u32x4*)(H + (size_t)tok * 1024 + 64 * sub);
; #pragma unroll
;             for (int q = 0; q < 8; ++q) { const u32x4 w = hp[q];
;                 const float4 ga = *(const float4*)(gffn + 64 * sub + q * 8), gb = *(const float4*)(gffn + 64 * sub + q * 8 + 4);
;                 hf2[q * 4 + 0] = cvt_pk_bf16(bflo(w.x) * rstd * ga.x, bfhi(w.x) * rstd * ga.y);
;                 hf2[q * 4 + 1] = cvt_pk_bf16(bflo(w.y) * rstd * ga.z, bfhi(w.y) * rstd * ga.w);
;                 hf2[q * 4 + 2] = cvt_pk_bf16(bflo(w.z) * rstd * gb.x, bfhi(w.z) * rstd * gb.y);
;                 hf2[q * 4 + 3] = cvt_pk_bf16(bflo(w.w) * rstd * gb.z, bfhi(w.w) * rstd * gb.w); } }
	v_pk_mul_f32 v[2:3], v[2:3], v[12:13] op_sel_hi:[1,0]
	v_pk_mul_f32 v[4:5], v[4:5], v[12:13] op_sel_hi:[1,0]
	v_pk_mul_f32 v[2:3], v[2:3], v[114:115]
	v_pk_mul_f32 v[4:5], v[4:5], v[116:117]
	v_cvt_pk_bf16_f32 v204, v2, v3
	v_cvt_pk_bf16_f32 v205, v4, v5
	v_lshlrev_b32_e32 v2, 16, v210
	v_and_b32_e32 v3, 0xffff0000, v210
	v_lshlrev_b32_e32 v4, 16, v211
	v_and_b32_e32 v5, 0xffff0000, v211
	v_pk_mul_f32 v[2:3], v[2:3], v[12:13] op_sel_hi:[1,0]
	v_pk_mul_f32 v[4:5], v[4:5], v[12:13] op_sel_hi:[1,0]
	v_pk_mul_f32 v[2:3], v[2:3], v[118:119]
	v_pk_mul_f32 v[4:5], v[4:5], v[120:121]
	v_cvt_pk_bf16_f32 v206, v2, v3
	v_cvt_pk_bf16_f32 v207, v4, v5
	v_readlane_b32 s0, v251, 29
	s_nop 3
	v_add_u32_e32 v72, s0, v72
	v_ashrrev_i32_e32 v73, 31, v72
	v_readlane_b32 s0, v253, 24
	v_lshlrev_b64 v[0:1], 11, v[72:73]
	v_readlane_b32 s1, v253, 25
	v_lshlrev_b64 v[88:89], 10, v[72:73]
	v_mov_b32_e32 v156, 0
	v_lshl_add_u64 v[0:1], s[0:1], 0, v[0:1]
	v_lshl_add_u64 v[6:7], v[0:1], 0, v[128:129]
	global_load_dwordx4 v[2:5], v[6:7], off
	global_load_dwordx4 v[122:125], v[6:7], off offset:1024
	v_add_co_u32_e32 v216, vcc, v0, v94
	s_nop 1
	v_addc_co_u32_e32 v217, vcc, 0, v1, vcc
	global_load_dwordx4 v[218:221], v[216:217], off offset:0
	global_load_dwordx4 v[222:225], v[216:217], off offset:16
	global_load_dwordx4 v[226:229], v[216:217], off offset:32
	global_load_dwordx4 v[230:233], v[216:217], off offset:48
	global_load_dwordx4 v[234:237], v[216:217], off offset:64
	global_load_dwordx4 v[238:241], v[216:217], off offset:80
	global_load_dwordx4 v[242:245], v[216:217], off offset:96
	global_load_dwordx4 v[246:249], v[216:217], off offset:112
	global_load_dwordx4 v[32:35], v[78:79], off offset:32
	global_load_dwordx4 v[36:39], v[78:79], off offset:48
	global_load_dwordx4 v[40:43], v[78:79], off offset:64
	global_load_dwordx4 v[44:47], v[78:79], off offset:80
	global_load_dwordx4 v[48:51], v[78:79], off offset:96
	global_load_dwordx4 v[52:55], v[78:79], off offset:112
	global_load_dwordx4 v[56:59], v[78:79], off offset:128
	global_load_dwordx4 v[60:63], v[78:79], off offset:144
	global_load_dwordx4 v[98:101], v[78:79], off offset:160
	global_load_dwordx4 v[102:105], v[78:79], off offset:176
	global_load_dwordx4 v[106:109], v[78:79], off offset:192
	global_load_dwordx4 v[110:113], v[78:79], off offset:208
	global_load_dwordx4 v[114:117], v[78:79], off offset:224
	global_load_dwordx4 v[118:121], v[78:79], off offset:240
	v_mov_b32_e32 v157, 0
	v_mov_b32_e32 v158, 0
	s_waitcnt vmcnt(23)
	v_lshlrev_b32_e32 v8, 16, v2
	v_and_b32_e32 v2, 0xffff0000, v2
	v_mul_f32_e32 v2, v2, v2
	v_fmac_f32_e32 v2, v8, v8
	v_lshlrev_b32_e32 v8, 16, v3
	v_and_b32_e32 v3, 0xffff0000, v3
	v_mul_f32_e32 v3, v3, v3
	v_fmac_f32_e32 v3, v8, v8
	v_add_f32_e32 v8, v2, v3
	v_lshlrev_b32_e32 v3, 16, v5
	v_lshlrev_b32_e32 v2, 16, v4
	v_and_b32_e32 v5, 0xffff0000, v5
	v_and_b32_e32 v4, 0xffff0000, v4
	v_pk_mul_f32 v[4:5], v[4:5], v[4:5]
	s_nop 0
	v_pk_fma_f32 v[2:3], v[2:3], v[2:3], v[4:5]
	s_nop 0
	v_add_f32_e32 v2, v2, v8
	v_add_f32_e32 v8, v3, v2
	s_waitcnt vmcnt(22)
	v_mov_b32_e32 v2, v122
	v_mov_b32_e32 v3, v123
	v_mov_b32_e32 v4, v124
	v_mov_b32_e32 v5, v125
	v_lshlrev_b32_e32 v7, 16, v3
	v_lshlrev_b32_e32 v6, 16, v2
	v_and_b32_e32 v3, 0xffff0000, v3
	v_and_b32_e32 v2, 0xffff0000, v2
	v_pk_mul_f32 v[2:3], v[2:3], v[2:3]
	s_nop 0
	v_pk_fma_f32 v[2:3], v[6:7], v[6:7], v[2:3]
	s_nop 0
	v_add_f32_e32 v2, v2, v8
	v_add_f32_e32 v6, v3, v2
	v_lshlrev_b32_e32 v3, 16, v5
	v_lshlrev_b32_e32 v2, 16, v4
	v_and_b32_e32 v5, 0xffff0000, v5
	v_and_b32_e32 v4, 0xffff0000, v4
	v_pk_mul_f32 v[4:5], v[4:5], v[4:5]
	s_nop 0
	v_pk_fma_f32 v[2:3], v[2:3], v[2:3], v[4:5]
	s_nop 0
	v_add_f32_e32 v2, v2, v6
	v_add_f32_e32 v2, v3, v2
	s_nop 1
	v_add_f32_dpp v2, v2, v2 quad_perm:[1,0,3,2] row_mask:0xf bank_mask:0xf bound_ctrl:1
	s_nop 1
	v_add_f32_dpp v2, v2, v2 quad_perm:[2,3,0,1] row_mask:0xf bank_mask:0xf bound_ctrl:1
	s_nop 1
	v_add_f32_dpp v2, v2, v2 row_half_mirror row_mask:0xf bank_mask:0xf bound_ctrl:1
	s_nop 1
	v_add_f32_dpp v2, v2, v2 row_mirror row_mask:0xf bank_mask:0xf bound_ctrl:1
	s_nop 0
	v_readlane_b32 s2, v2, 16
	v_readlane_b32 s6, v2, 48
	v_readlane_b32 s0, v2, 0
	v_readlane_b32 s1, v2, 32
	v_mov_b32_e32 v2, s2
	v_mov_b32_e32 v3, s6
	v_pk_add_f32 v[2:3], s[0:1], v[2:3]
	s_mov_b32 s0, 0x800000
	v_add_f32_e32 v2, v2, v3
	v_fmamk_f32 v2, v2, 0x3a800000, v170
	v_cmp_gt_f32_e32 vcc, s0, v2
	v_mul_f32_e32 v3, 0x4b800000, v2
	s_mov_b32 s6, 0
	v_cndmask_b32_e32 v2, v2, v3, vcc
	v_rsq_f32_e32 v2, v2
	s_nop 0
	v_mul_f32_e32 v3, 0x45800000, v2
	v_cndmask_b32_e32 v12, v2, v3, vcc
	v_lshlrev_b64 v[2:3], 13, v[72:73]
	v_lshl_add_u64 v[2:3], v[92:93], 0, v[2:3]
	v_mov_b32_e32 v73, 0
; __device__ __forceinline__ float key2f(unsigned k) { return __uint_as_float((k & 0x80000000u) ? (k & 0x7fffffffu) : ~k); }
; __device__ void ph_peer(const float* __restrict__ SC, const bf16_t* __restrict__ H  , const float* __restrict__ gffn, const unsigned char* __restrict__ U, const unsigned char* __restrict__ V, float* X, const float* __restrict__ fgain) {
;     ...
;             for (int u = 0; u < 2; ++u) {
;                 const float bs = key2f(best[u] & ~255u);
;                 const int pos = 255 - (int)(best[u] & 255u);
;                 const int e0 = __shfl(n0[u], (pos >> 4) & 15), e1 = __shfl(n1[u], pos & 15);
;                 const float mxs = __shfl(bs, 0);
;                 float e = lane < 16 ? __expf((bs - mxs) * rstd) : 0.f;
;                 const float den = row16_sum(e);
;                 const int iv = __shfl(e0 * 128 + e1, lane & 15); const float gv = __shfl(e / den, lane & 15);
;                 const int hh = h + u;
;                 if (grp == (hh & 3)) { if (hh < 4) { idx_lo = iv; g_lo = gv; } else { idx_hi = iv; g_hi = gv; } } }
.Lpeer_partB_b:
	v_lshrrev_b32_e32 v2, 11, v72
	v_lshrrev_b32_e32 v3, 6, v131
	v_lshl_add_u32 v2, v2, 3, v91
	v_mul_u32_u24_e32 v3, 0x1c00, v3
	v_mul_u32_u24_e32 v2, 0x70, v2
	v_and_b32_e32 v4, 15, v74
	v_add_u32_e32 v3, 0x12000, v3
	v_add_u32_e32 v2, v3, v2
	v_add_u32_e32 v5, v2, v4
	v_lshl_add_u32 v6, v4, 2, v2
	ds_read_u8 v7, v5 offset:96
	ds_read_u8 v8, v5 offset:544
	ds_read_b32 v9, v6 offset:32
	ds_read_b32 v10, v6 offset:480
	ds_read_b32 v11, v2 offset:32
	ds_read_b32 v13, v2 offset:480
	s_waitcnt lgkmcnt(4)
	v_not_b32_e32 v7, v7
	v_not_b32_e32 v8, v8
	v_bfe_u32 v14, v7, 4, 4
	v_and_b32_e32 v7, 15, v7
	v_bfe_u32 v15, v8, 4, 4
	v_and_b32_e32 v8, 15, v8
	v_add_u32_e32 v14, v2, v14
	v_add_u32_e32 v7, v2, v7
	v_add_u32_e32 v15, v2, v15
	v_add_u32_e32 v8, v2, v8
	ds_read_u8 v14, v14
	ds_read_u8 v7, v7 offset:16
	ds_read_u8 v15, v15 offset:448
	ds_read_u8 v8, v8 offset:464
	s_waitcnt lgkmcnt(4)
	v_sub_f32_e32 v9, v9, v11
	v_sub_f32_e32 v10, v10, v13
	v_mul_f32_e32 v9, v12, v9
	v_mul_f32_e32 v10, v12, v10
	v_mul_f32_e32 v9, 0x3fb8aa3b, v9
	v_mul_f32_e32 v10, 0x3fb8aa3b, v10
	v_exp_f32_e32 v9, v9
	v_exp_f32_e32 v10, v10
	s_nop 1
	v_add_f32_dpp v11, v9, v9 quad_perm:[1,0,3,2] row_mask:0xf bank_mask:0xf bound_ctrl:1
	v_add_f32_dpp v13, v10, v10 quad_perm:[1,0,3,2] row_mask:0xf bank_mask:0xf bound_ctrl:1
	s_nop 0
	v_add_f32_dpp v11, v11, v11 quad_perm:[2,3,0,1] row_mask:0xf bank_mask:0xf bound_ctrl:1
	v_add_f32_dpp v13, v13, v13 quad_perm:[2,3,0,1] row_mask:0xf bank_mask:0xf bound_ctrl:1
	s_nop 0
	v_add_f32_dpp v11, v11, v11 row_half_mirror row_mask:0xf bank_mask:0xf bound_ctrl:1
	v_add_f32_dpp v13, v13, v13 row_half_mirror row_mask:0xf bank_mask:0xf bound_ctrl:1
	s_nop 0
	v_add_f32_dpp v11, v11, v11 row_mirror row_mask:0xf bank_mask:0xf bound_ctrl:1
	v_add_f32_dpp v13, v13, v13 row_mirror row_mask:0xf bank_mask:0xf bound_ctrl:1
	s_nop 0
	v_div_scale_f32 v16, s[0:1], v11, v11, v9
	v_div_scale_f32 v17, s[0:1], v13, v13, v10
	v_rcp_f32_e32 v18, v16
	v_rcp_f32_e32 v19, v17
	s_nop 0
	v_fma_f32 v20, -v16, v18, 1.0
	v_fma_f32 v21, -v17, v19, 1.0
	v_fmac_f32_e32 v18, v20, v18
	v_fmac_f32_e32 v19, v21, v19
	v_div_scale_f32 v20, vcc, v9, v11, v9
	v_mul_f32_e32 v22, v20, v18
	v_fma_f32 v24, -v16, v22, v20
	v_fmac_f32_e32 v22, v24, v18
	v_fma_f32 v20, -v16, v22, v20
	v_div_fmas_f32 v20, v20, v18, v22
	v_div_fixup_f32 v73, v20, v11, v9
	v_div_scale_f32 v21, vcc, v10, v13, v10
	v_mul_f32_e32 v23, v21, v19
	v_fma_f32 v25, -v17, v23, v21
	v_fmac_f32_e32 v23, v25, v19
	v_fma_f32 v21, -v17, v23, v21
	v_div_fmas_f32 v21, v21, v19, v23
	v_div_fixup_f32 v158, v21, v13, v10
	s_waitcnt lgkmcnt(0)
	v_and_b32_e32 v14, 0x7f, v14
	v_and_b32_e32 v7, 0x7f, v7
	v_and_b32_e32 v15, 0x7f, v15
	v_and_b32_e32 v8, 0x7f, v8
	v_lshl_or_b32 v14, v14, 7, v7
	v_lshl_or_b32 v15, v15, 7, v8
	v_xor_b32_e32 v156, 0x3fff, v14
	v_xor_b32_e32 v157, 0x3fff, v15
	v_lshrrev_b32_e32 v2, 11, v156
	v_lshrrev_b32_e32 v3, 11, v157
	s_mov_b32 s2, 0
	v_mov_b32_e32 v6, 0
	v_mov_b32_e32 v7, 0
	v_cmp_eq_u32_e64 s[0:1], 0, v2
	v_cmp_eq_u32_e64 s[6:7], 0, v3
	s_nop 1
	v_mbcnt_lo_u32_b32 v4, s0, 0
	v_mbcnt_lo_u32_b32 v5, s6, 0
	v_mbcnt_hi_u32_b32 v4, s1, v4
	v_mbcnt_hi_u32_b32 v5, s7, v5
	s_bcnt1_i32_b64 s14, s[0:1]
	s_bcnt1_i32_b64 s15, s[6:7]
	v_add_u32_e32 v4, s2, v4
	s_add_i32 s14, s2, s14
	s_nop 0
	v_add_u32_e32 v5, s14, v5
	s_add_i32 s2, s14, s15
	v_cndmask_b32_e64 v6, v6, v4, s[0:1]
	v_cndmask_b32_e64 v7, v7, v5, s[6:7]
	v_cmp_eq_u32_e64 s[0:1], 1, v2
	v_cmp_eq_u32_e64 s[6:7], 1, v3
	s_nop 1
	v_mbcnt_lo_u32_b32 v4, s0, 0
	v_mbcnt_lo_u32_b32 v5, s6, 0
	v_mbcnt_hi_u32_b32 v4, s1, v4
	v_mbcnt_hi_u32_b32 v5, s7, v5
	s_bcnt1_i32_b64 s14, s[0:1]
	s_bcnt1_i32_b64 s15, s[6:7]
	v_add_u32_e32 v4, s2, v4
	s_add_i32 s14, s2, s14
	s_nop 0
	v_add_u32_e32 v5, s14, v5
	s_add_i32 s2, s14, s15
	v_cndmask_b32_e64 v6, v6, v4, s[0:1]
	v_cndmask_b32_e64 v7, v7, v5, s[6:7]
	v_cmp_eq_u32_e64 s[0:1], 2, v2
	v_cmp_eq_u32_e64 s[6:7], 2, v3
	s_nop 1
	v_mbcnt_lo_u32_b32 v4, s0, 0
	v_mbcnt_lo_u32_b32 v5, s6, 0
	v_mbcnt_hi_u32_b32 v4, s1, v4
	v_mbcnt_hi_u32_b32 v5, s7, v5
	s_bcnt1_i32_b64 s14, s[0:1]
	s_bcnt1_i32_b64 s15, s[6:7]
	v_add_u32_e32 v4, s2, v4
	s_add_i32 s14, s2, s14
	s_nop 0
	v_add_u32_e32 v5, s14, v5
	s_add_i32 s2, s14, s15
	v_cndmask_b32_e64 v6, v6, v4, s[0:1]
	v_cndmask_b32_e64 v7, v7, v5, s[6:7]
	v_cmp_eq_u32_e64 s[0:1], 3, v2
	v_cmp_eq_u32_e64 s[6:7], 3, v3
	s_nop 1
	v_mbcnt_lo_u32_b32 v4, s0, 0
	v_mbcnt_lo_u32_b32 v5, s6, 0
	v_mbcnt_hi_u32_b32 v4, s1, v4
	v_mbcnt_hi_u32_b32 v5, s7, v5
	s_bcnt1_i32_b64 s14, s[0:1]
	s_bcnt1_i32_b64 s15, s[6:7]
	v_add_u32_e32 v4, s2, v4
	s_add_i32 s14, s2, s14
	s_nop 0
	v_add_u32_e32 v5, s14, v5
	s_add_i32 s2, s14, s15
	v_cndmask_b32_e64 v6, v6, v4, s[0:1]
	v_cndmask_b32_e64 v7, v7, v5, s[6:7]
	v_cmp_eq_u32_e64 s[0:1], 4, v2
	v_cmp_eq_u32_e64 s[6:7], 4, v3
	s_nop 1
	v_mbcnt_lo_u32_b32 v4, s0, 0
	v_mbcnt_lo_u32_b32 v5, s6, 0
	v_mbcnt_hi_u32_b32 v4, s1, v4
	v_mbcnt_hi_u32_b32 v5, s7, v5
	s_bcnt1_i32_b64 s14, s[0:1]
	s_bcnt1_i32_b64 s15, s[6:7]
	v_add_u32_e32 v4, s2, v4
	s_add_i32 s14, s2, s14
	s_nop 0
	v_add_u32_e32 v5, s14, v5
	s_add_i32 s2, s14, s15
	v_cndmask_b32_e64 v6, v6, v4, s[0:1]
	v_cndmask_b32_e64 v7, v7, v5, s[6:7]
	v_cmp_eq_u32_e64 s[0:1], 5, v2
	v_cmp_eq_u32_e64 s[6:7], 5, v3
	s_nop 1
	v_mbcnt_lo_u32_b32 v4, s0, 0
	v_mbcnt_lo_u32_b32 v5, s6, 0
	v_mbcnt_hi_u32_b32 v4, s1, v4
	v_mbcnt_hi_u32_b32 v5, s7, v5
	s_bcnt1_i32_b64 s14, s[0:1]
	s_bcnt1_i32_b64 s15, s[6:7]
	v_add_u32_e32 v4, s2, v4
	s_add_i32 s14, s2, s14
	s_nop 0
	v_add_u32_e32 v5, s14, v5
	s_add_i32 s2, s14, s15
	v_cndmask_b32_e64 v6, v6, v4, s[0:1]
	v_cndmask_b32_e64 v7, v7, v5, s[6:7]
	v_cmp_eq_u32_e64 s[0:1], 6, v2
	v_cmp_eq_u32_e64 s[6:7], 6, v3
	s_nop 1
	v_mbcnt_lo_u32_b32 v4, s0, 0
	v_mbcnt_lo_u32_b32 v5, s6, 0
	v_mbcnt_hi_u32_b32 v4, s1, v4
	v_mbcnt_hi_u32_b32 v5, s7, v5
	s_bcnt1_i32_b64 s14, s[0:1]
	s_bcnt1_i32_b64 s15, s[6:7]
	v_add_u32_e32 v4, s2, v4
	s_add_i32 s14, s2, s14
	s_nop 0
	v_add_u32_e32 v5, s14, v5
	s_add_i32 s2, s14, s15
	v_cndmask_b32_e64 v6, v6, v4, s[0:1]
	v_cndmask_b32_e64 v7, v7, v5, s[6:7]
	v_cmp_eq_u32_e64 s[0:1], 7, v2
	v_cmp_eq_u32_e64 s[6:7], 7, v3
	s_nop 1
	v_mbcnt_lo_u32_b32 v4, s0, 0
	v_mbcnt_lo_u32_b32 v5, s6, 0
	v_mbcnt_hi_u32_b32 v4, s1, v4
	v_mbcnt_hi_u32_b32 v5, s7, v5
	s_bcnt1_i32_b64 s14, s[0:1]
	s_bcnt1_i32_b64 s15, s[6:7]
	v_add_u32_e32 v4, s2, v4
	s_add_i32 s14, s2, s14
	s_nop 0
	v_add_u32_e32 v5, s14, v5
	s_add_i32 s2, s14, s15
	v_cndmask_b32_e64 v6, v6, v4, s[0:1]
	v_cndmask_b32_e64 v7, v7, v5, s[6:7]
	v_lshrrev_b32_e32 v8, 6, v131
	v_mul_u32_u24_e32 v8, 0x2400, v8
	v_lshl_add_u32 v9, v6, 2, v8
	v_lshl_add_u32 v10, v7, 2, v8
	ds_write_b32 v9, v156 offset:1536
	ds_write_b32 v10, v157 offset:1536
	ds_write_b32 v9, v73 offset:2048
	ds_write_b32 v10, v158 offset:2048
	s_waitcnt vmcnt(0) lgkmcnt(0)
; __device__ __forceinline__ unsigned cvt_pk_bf16(float lo, float hi) { unsigned r; asm volatile("v_cvt_pk_bf16_f32 %0, %1, %2" : "=v"(r) : "v"(lo), "v"(hi)); return r; }
; __device__ __forceinline__ float bflo(unsigned w) { return __uint_as_float(w << 16); }
; __device__ __forceinline__ float bfhi(unsigned w) { return __uint_as_float(w & 0xffff0000u); }
; __device__ void ph_peer(const float* __restrict__ SC, const bf16_t* __restrict__ H  , const float* __restrict__ gffn, const unsigned char* __restrict__ U, const unsigned char* __restrict__ V, float* X, const float* __restrict__ fgain) {
;     ...
;         {   const u32x4* hp = (const u32x4*)(H + (size_t)tok * 1024 + 64 * sub);
; #pragma unroll
;             for (int q = 0; q < 8; ++q) { const u32x4 w = hp[q];
;                 const float4 ga = *(const float4*)(gffn + 64 * sub + q * 8), gb = *(const float4*)(gffn + 64 * sub + q * 8 + 4);
;                 hf2[q * 4 + 0] = cvt_pk_bf16(bflo(w.x) * rstd * ga.x, bfhi(w.x) * rstd * ga.y);
;                 hf2[q * 4 + 1] = cvt_pk_bf16(bflo(w.y) * rstd * ga.z, bfhi(w.y) * rstd * ga.w);
;                 hf2[q * 4 + 2] = cvt_pk_bf16(bflo(w.z) * rstd * gb.x, bfhi(w.z) * rstd * gb.y);
;                 hf2[q * 4 + 3] = cvt_pk_bf16(bflo(w.w) * rstd * gb.z, bfhi(w.w) * rstd * gb.w); } }
	v_lshlrev_b32_e32 v2, 16, v218
	v_and_b32_e32 v3, 0xffff0000, v218
	v_lshlrev_b32_e32 v4, 16, v219
	v_and_b32_e32 v5, 0xffff0000, v219
	v_pk_mul_f32 v[2:3], v[2:3], v[12:13] op_sel_hi:[1,0]
	v_pk_mul_f32 v[4:5], v[4:5], v[12:13] op_sel_hi:[1,0]
	v_pk_mul_f32 v[2:3], v[2:3], v[64:65]
	v_pk_mul_f32 v[4:5], v[4:5], v[66:67]
	v_cvt_pk_bf16_f32 v212, v2, v3
	v_cvt_pk_bf16_f32 v213, v4, v5
	v_lshlrev_b32_e32 v2, 16, v220
	v_and_b32_e32 v3, 0xffff0000, v220
	v_lshlrev_b32_e32 v4, 16, v221
	v_and_b32_e32 v5, 0xffff0000, v221
	v_pk_mul_f32 v[2:3], v[2:3], v[12:13] op_sel_hi:[1,0]
	v_pk_mul_f32 v[4:5], v[4:5], v[12:13] op_sel_hi:[1,0]
	v_pk_mul_f32 v[2:3], v[2:3], v[68:69]
	v_pk_mul_f32 v[4:5], v[4:5], v[70:71]
	v_cvt_pk_bf16_f32 v214, v2, v3
	v_cvt_pk_bf16_f32 v215, v4, v5
	v_lshlrev_b32_e32 v2, 16, v222
	v_and_b32_e32 v3, 0xffff0000, v222
	v_lshlrev_b32_e32 v4, 16, v223
	v_and_b32_e32 v5, 0xffff0000, v223
	v_pk_mul_f32 v[2:3], v[2:3], v[12:13] op_sel_hi:[1,0]
	v_pk_mul_f32 v[4:5], v[4:5], v[12:13] op_sel_hi:[1,0]
	v_pk_mul_f32 v[2:3], v[2:3], v[32:33]
	v_pk_mul_f32 v[4:5], v[4:5], v[34:35]
	v_cvt_pk_bf16_f32 v218, v2, v3
	v_cvt_pk_bf16_f32 v219, v4, v5
	v_lshlrev_b32_e32 v2, 16, v224
	v_and_b32_e32 v3, 0xffff0000, v224
	v_lshlrev_b32_e32 v4, 16, v225
	v_and_b32_e32 v5, 0xffff0000, v225
	v_pk_mul_f32 v[2:3], v[2:3], v[12:13] op_sel_hi:[1,0]
	v_pk_mul_f32 v[4:5], v[4:5], v[12:13] op_sel_hi:[1,0]
	v_pk_mul_f32 v[2:3], v[2:3], v[36:37]
	v_pk_mul_f32 v[4:5], v[4:5], v[38:39]
	v_cvt_pk_bf16_f32 v220, v2, v3
	v_cvt_pk_bf16_f32 v221, v4, v5
	v_lshlrev_b32_e32 v2, 16, v226
	v_and_b32_e32 v3, 0xffff0000, v226
	v_lshlrev_b32_e32 v4, 16, v227
	v_and_b32_e32 v5, 0xffff0000, v227
	v_pk_mul_f32 v[2:3], v[2:3], v[12:13] op_sel_hi:[1,0]
	v_pk_mul_f32 v[4:5], v[4:5], v[12:13] op_sel_hi:[1,0]
	v_pk_mul_f32 v[2:3], v[2:3], v[40:41]
	v_pk_mul_f32 v[4:5], v[4:5], v[42:43]
	v_cvt_pk_bf16_f32 v222, v2, v3
	v_cvt_pk_bf16_f32 v223, v4, v5
	v_lshlrev_b32_e32 v2, 16, v228
	v_and_b32_e32 v3, 0xffff0000, v228
	v_lshlrev_b32_e32 v4, 16, v229
	v_and_b32_e32 v5, 0xffff0000, v229
	v_pk_mul_f32 v[2:3], v[2:3], v[12:13] op_sel_hi:[1,0]
	v_pk_mul_f32 v[4:5], v[4:5], v[12:13] op_sel_hi:[1,0]
	v_pk_mul_f32 v[2:3], v[2:3], v[44:45]
	v_pk_mul_f32 v[4:5], v[4:5], v[46:47]
	v_cvt_pk_bf16_f32 v224, v2, v3
	v_cvt_pk_bf16_f32 v225, v4, v5
	v_lshlrev_b32_e32 v2, 16, v230
	v_and_b32_e32 v3, 0xffff0000, v230
	v_lshlrev_b32_e32 v4, 16, v231
	v_and_b32_e32 v5, 0xffff0000, v231
	v_pk_mul_f32 v[2:3], v[2:3], v[12:13] op_sel_hi:[1,0]
	v_pk_mul_f32 v[4:5], v[4:5], v[12:13] op_sel_hi:[1,0]
	v_pk_mul_f32 v[2:3], v[2:3], v[48:49]
	v_pk_mul_f32 v[4:5], v[4:5], v[50:51]
	v_cvt_pk_bf16_f32 v226, v2, v3
	v_cvt_pk_bf16_f32 v227, v4, v5
	v_lshlrev_b32_e32 v2, 16, v232
	v_and_b32_e32 v3, 0xffff0000, v232
	v_lshlrev_b32_e32 v4, 16, v233
	v_and_b32_e32 v5, 0xffff0000, v233
	v_pk_mul_f32 v[2:3], v[2:3], v[12:13] op_sel_hi:[1,0]
	v_pk_mul_f32 v[4:5], v[4:5], v[12:13] op_sel_hi:[1,0]
	v_pk_mul_f32 v[2:3], v[2:3], v[52:53]
	v_pk_mul_f32 v[4:5], v[4:5], v[54:55]
	v_cvt_pk_bf16_f32 v228, v2, v3
	v_cvt_pk_bf16_f32 v229, v4, v5
	v_lshlrev_b32_e32 v2, 16, v234
	v_and_b32_e32 v3, 0xffff0000, v234
	v_lshlrev_b32_e32 v4, 16, v235
	v_and_b32_e32 v5, 0xffff0000, v235
	v_pk_mul_f32 v[2:3], v[2:3], v[12:13] op_sel_hi:[1,0]
	v_pk_mul_f32 v[4:5], v[4:5], v[12:13] op_sel_hi:[1,0]
	v_pk_mul_f32 v[2:3], v[2:3], v[56:57]
	v_pk_mul_f32 v[4:5], v[4:5], v[58:59]
	v_cvt_pk_bf16_f32 v230, v2, v3
	v_cvt_pk_bf16_f32 v231, v4, v5
	v_lshlrev_b32_e32 v2, 16, v236
	v_and_b32_e32 v3, 0xffff0000, v236
	v_lshlrev_b32_e32 v4, 16, v237
	v_and_b32_e32 v5, 0xffff0000, v237
	v_pk_mul_f32 v[2:3], v[2:3], v[12:13] op_sel_hi:[1,0]
	v_pk_mul_f32 v[4:5], v[4:5], v[12:13] op_sel_hi:[1,0]
	v_pk_mul_f32 v[2:3], v[2:3], v[60:61]
	v_pk_mul_f32 v[4:5], v[4:5], v[62:63]
	v_cvt_pk_bf16_f32 v232, v2, v3
; __device__ __forceinline__ unsigned cvt_pk_bf16(float lo, float hi) { unsigned r; asm volatile("v_cvt_pk_bf16_f32 %0, %1, %2" : "=v"(r) : "v"(lo), "v"(hi)); return r; }
; __device__ __forceinline__ float bflo(unsigned w) { return __uint_as_float(w << 16); }
; __device__ __forceinline__ float bfhi(unsigned w) { return __uint_as_float(w & 0xffff0000u); }
; __device__ void ph_peer(const float* __restrict__ SC, const bf16_t* __restrict__ H  , const float* __restrict__ gffn, const unsigned char* __restrict__ U, const unsigned char* __restrict__ V, float* X, const float* __restrict__ fgain) {
;     ...
;         {   const u32x4* hp = (const u32x4*)(H + (size_t)tok * 1024 + 64 * sub);
; #pragma unroll
;             for (int q = 0; q < 8; ++q) { const u32x4 w = hp[q];
;                 const float4 ga = *(const float4*)(gffn + 64 * sub + q * 8), gb = *(const float4*)(gffn + 64 * sub + q * 8 + 4);
;                 hf2[q * 4 + 0] = cvt_pk_bf16(bflo(w.x) * rstd * ga.x, bfhi(w.x) * rstd * ga.y);
;                 hf2[q * 4 + 1] = cvt_pk_bf16(bflo(w.y) * rstd * ga.z, bfhi(w.y) * rstd * ga.w);
;                 hf2[q * 4 + 2] = cvt_pk_bf16(bflo(w.z) * rstd * gb.x, bfhi(w.z) * rstd * gb.y);
;                 hf2[q * 4 + 3] = cvt_pk_bf16(bflo(w.w) * rstd * gb.z, bfhi(w.w) * rstd * gb.w); } }
;         const int half = lane >> 5, c32 = lane & 31;
;         float acc[32];
; #pragma unroll
;         for (int i = 0; i < 32; ++i) acc[i] = 0.f;
;         __builtin_amdgcn_s_setprio(1);
; #pragma unroll 1
;         for (int it = 0; it < 32; ++it) {
;             const int src = (it * 4 + grp) & 63;
;             const int e = __shfl(it < 16 ? idx_lo : idx_hi, src);
;             const float gt = __shfl(it < 16 ? g_lo : g_hi, src);
;             const u32x4* up = (const u32x4*)(U + (size_t)e * 768 + 48 * sub);
;             const u32x4 u0 = up[0], u1 = up[1], u2 = up[2];
	v_cvt_pk_bf16_f32 v233, v4, v5
	v_lshlrev_b32_e32 v2, 16, v238
	v_and_b32_e32 v3, 0xffff0000, v238
	v_lshlrev_b32_e32 v4, 16, v239
	v_and_b32_e32 v5, 0xffff0000, v239
	v_pk_mul_f32 v[2:3], v[2:3], v[12:13] op_sel_hi:[1,0]
	v_pk_mul_f32 v[4:5], v[4:5], v[12:13] op_sel_hi:[1,0]
	v_pk_mul_f32 v[2:3], v[2:3], v[98:99]
	v_pk_mul_f32 v[4:5], v[4:5], v[100:101]
	v_cvt_pk_bf16_f32 v234, v2, v3
	v_cvt_pk_bf16_f32 v235, v4, v5
	v_lshlrev_b32_e32 v2, 16, v240
	v_and_b32_e32 v3, 0xffff0000, v240
	v_lshlrev_b32_e32 v4, 16, v241
	v_and_b32_e32 v5, 0xffff0000, v241
	v_pk_mul_f32 v[2:3], v[2:3], v[12:13] op_sel_hi:[1,0]
	v_pk_mul_f32 v[4:5], v[4:5], v[12:13] op_sel_hi:[1,0]
	v_pk_mul_f32 v[2:3], v[2:3], v[102:103]
	v_pk_mul_f32 v[4:5], v[4:5], v[104:105]
	v_cvt_pk_bf16_f32 v236, v2, v3
	v_cvt_pk_bf16_f32 v237, v4, v5
	v_lshlrev_b32_e32 v2, 16, v242
	v_and_b32_e32 v3, 0xffff0000, v242
	v_lshlrev_b32_e32 v4, 16, v243
	v_and_b32_e32 v5, 0xffff0000, v243
	v_pk_mul_f32 v[2:3], v[2:3], v[12:13] op_sel_hi:[1,0]
	v_pk_mul_f32 v[4:5], v[4:5], v[12:13] op_sel_hi:[1,0]
	v_pk_mul_f32 v[2:3], v[2:3], v[106:107]
	v_pk_mul_f32 v[4:5], v[4:5], v[108:109]
	v_cvt_pk_bf16_f32 v238, v2, v3
	v_cvt_pk_bf16_f32 v239, v4, v5
	v_lshlrev_b32_e32 v2, 16, v244
	v_and_b32_e32 v3, 0xffff0000, v244
	v_lshlrev_b32_e32 v4, 16, v245
	v_and_b32_e32 v5, 0xffff0000, v245
	v_pk_mul_f32 v[2:3], v[2:3], v[12:13] op_sel_hi:[1,0]
	v_pk_mul_f32 v[4:5], v[4:5], v[12:13] op_sel_hi:[1,0]
	v_pk_mul_f32 v[2:3], v[2:3], v[110:111]
	v_pk_mul_f32 v[4:5], v[4:5], v[112:113]
	v_cvt_pk_bf16_f32 v240, v2, v3
	v_cvt_pk_bf16_f32 v241, v4, v5
	v_lshlrev_b32_e32 v2, 16, v246
	v_and_b32_e32 v3, 0xffff0000, v246
	v_lshlrev_b32_e32 v4, 16, v247
	v_and_b32_e32 v5, 0xffff0000, v247
	v_pk_mul_f32 v[2:3], v[2:3], v[12:13] op_sel_hi:[1,0]
	v_pk_mul_f32 v[4:5], v[4:5], v[12:13] op_sel_hi:[1,0]
	v_pk_mul_f32 v[2:3], v[2:3], v[114:115]
	v_pk_mul_f32 v[4:5], v[4:5], v[116:117]
	v_cvt_pk_bf16_f32 v242, v2, v3
	v_cvt_pk_bf16_f32 v243, v4, v5
	v_lshlrev_b32_e32 v2, 16, v248
	v_and_b32_e32 v3, 0xffff0000, v248
	v_lshlrev_b32_e32 v4, 16, v249
	v_and_b32_e32 v5, 0xffff0000, v249
	v_pk_mul_f32 v[2:3], v[2:3], v[12:13] op_sel_hi:[1,0]
	v_pk_mul_f32 v[4:5], v[4:5], v[12:13] op_sel_hi:[1,0]
	v_pk_mul_f32 v[2:3], v[2:3], v[118:119]
	v_pk_mul_f32 v[4:5], v[4:5], v[120:121]
	v_cvt_pk_bf16_f32 v244, v2, v3
	v_cvt_pk_bf16_f32 v245, v4, v5
	s_setprio 1
	v_mov_b32_e32 v126, 0
	s_mov_b32 s0, 0
	s_mov_b32 s1, 0
	v_mov_b32_e32 v127, v126
	v_mov_b32_e32 v144, v126
	v_mov_b32_e32 v145, v126
	v_mov_b32_e32 v122, v126
	v_mov_b32_e32 v123, v126
	v_mov_b32_e32 v124, v126
	v_mov_b32_e32 v125, v126
	v_mov_b32_e32 v114, v126
	v_mov_b32_e32 v115, v126
	v_mov_b32_e32 v118, v126
	v_mov_b32_e32 v119, v126
	v_mov_b32_e32 v116, v126
	v_mov_b32_e32 v117, v126
	v_mov_b32_e32 v120, v126
	v_mov_b32_e32 v121, v126
	v_mov_b32_e32 v106, v126
	v_mov_b32_e32 v107, v126
	v_mov_b32_e32 v110, v126
	v_mov_b32_e32 v111, v126
	v_mov_b32_e32 v108, v126
	v_mov_b32_e32 v109, v126
	v_mov_b32_e32 v112, v126
	v_mov_b32_e32 v113, v126
	v_mov_b32_e32 v98, v126
	v_mov_b32_e32 v99, v126
	v_mov_b32_e32 v102, v126
	v_mov_b32_e32 v103, v126
	v_mov_b32_e32 v100, v126
	v_mov_b32_e32 v101, v126
	v_mov_b32_e32 v104, v126
	v_mov_b32_e32 v105, v126
	s_movk_i32 s14, 0x300
	s_mov_b32 s16, 0x3e6d3388
	s_mov_b32 s24, 0x3f07dc22
	s_mov_b32 s28, 0x3f35f0e3
	s_mov_b32 s30, 0xbe11a98e
	s_mov_b32 s36, 0x3e027906
	s_barrier
	v_lshrrev_b32_e32 v61, 6, v131
	v_mul_u32_u24_e32 v61, 0x2400, v61
	v_lshl_add_u32 v61, v91, 2, v61
	s_mov_b32 s1, 0
	ds_read_b32 v56, v61
	ds_read_b32 v57, v61 offset:512
	v_add_u32_e32 v61, 16, v61
	s_add_i32 s1, s1, 1
	s_waitcnt lgkmcnt(1)
	v_mad_u32_u24 v0, v56, s14, v92
	global_load_dwordx4 v[32:35], v0, s[46:47]
	global_load_dwordx4 v[36:39], v0, s[46:47] offset:16
	global_load_dwordx4 v[40:43], v0, s[46:47] offset:32

; __device__ __forceinline__ unsigned cvt_pk_bf16(float lo, float hi) { unsigned r; asm volatile("v_cvt_pk_bf16_f32 %0, %1, %2" : "=v"(r) : "v"(lo), "v"(hi)); return r; }
; __device__ __forceinline__ float bflo(unsigned w) { return __uint_as_float(w << 16); }
; __device__ __forceinline__ float bfhi(unsigned w) { return __uint_as_float(w & 0xffff0000u); }
; __device__ void ph_gmlp(const bf16_t* __restrict__ PROJ, bf16_t* __restrict__ GA, const bf16_t* __restrict__ GWS  ,
;                         const float* __restrict__ lng, const float* __restrict__ lnb, const float* __restrict__ bs  , unsigned char* smem) {
;     ...
;             for (int j = 0; j < 4; ++j) { const int qd = tid + NTHR * j, pr = qd >> 4;
;                 vw[j] = *(const u32x4*)(PROJ + (size_t)(tok0 + pr) * 8192 + 1536 + g * 128 + dch * 8);
;                 ww[j] = *(const u32x4*)(GWS + (size_t)g * 16384 + (size_t)qd * 8); }
;             const float4 g0 = *(const float4*)(lng + g * 128 + dch * 8), g1 = *(const float4*)(lng + g * 128 + dch * 8 + 4);
;             const float4 b0 = *(const float4*)(lnb + g * 128 + dch * 8), b1 = *(const float4*)(lnb + g * 128 + dch * 8 + 4);
; #pragma unroll
;             for (int j = 0; j < 4; ++j) { const int qd = tid + NTHR * j, pr = qd >> 4; const u32x4 w = vw[j];
;                 const float mean = stats[pr * 2], rstd = stats[pr * 2 + 1];
;                 unsigned* dst = vt + pr * 65 + dch * 4;
;                 dst[0] = cvt_pk_bf16((bflo(w.x) - mean) * rstd * g0.x + b0.x, (bfhi(w.x) - mean) * rstd * g0.y + b0.y);
;                 dst[1] = cvt_pk_bf16((bflo(w.y) - mean) * rstd * g0.z + b0.z, (bfhi(w.y) - mean) * rstd * g0.w + b0.w);
;                 dst[2] = cvt_pk_bf16((bflo(w.z) - mean) * rstd * g1.x + b1.x, (bfhi(w.z) - mean) * rstd * g1.y + b1.y);
;                 dst[3] = cvt_pk_bf16((bflo(w.w) - mean) * rstd * g1.z + b1.z, (bfhi(w.w) - mean) * rstd * g1.w + b1.w);
;                 *(u32x4*)(wsl + (qd >> 4) * 136 + (qd & 15) * 8) = ww[j]; }
.LBB0_724:
	v_lshl_add_u64 v[0:1], s[22:23], 0, v[88:89]
	global_load_dwordx4 v[0:3], v[0:1], off
	v_lshl_add_u64 v[4:5], s[22:23], 0, v[68:69]
	v_lshl_add_u64 v[8:9], s[22:23], 0, v[86:87]
	v_lshl_add_u64 v[12:13], s[22:23], 0, v[70:71]
	v_lshl_add_u64 v[16:17], s[22:23], 0, v[84:85]
	v_lshl_add_u64 v[20:21], s[22:23], 0, v[72:73]
	v_lshl_add_u64 v[24:25], s[22:23], 0, v[82:83]
	v_lshl_add_u64 v[28:29], s[22:23], 0, v[74:75]
	v_lshl_add_u64 v[112:113], v[92:93], 0, s[26:27]
	v_lshl_add_u64 v[120:121], v[96:97], 0, s[26:27]
	global_load_dwordx4 v[4:7], v[4:5], off
	v_lshl_add_u64 v[68:69], v[68:69], 0, s[24:25]
	global_load_dwordx4 v[8:11], v[8:9], off
	v_lshl_add_u64 v[70:71], v[70:71], 0, s[24:25]
	global_load_dwordx4 v[12:15], v[12:13], off
	v_lshl_add_u64 v[72:73], v[72:73], 0, s[24:25]
	global_load_dwordx4 v[16:19], v[16:17], off
	v_lshl_add_u64 v[74:75], v[74:75], 0, s[24:25]
	global_load_dwordx4 v[20:23], v[20:21], off
	v_lshl_add_u64 v[82:83], v[82:83], 0, s[14:15]
	global_load_dwordx4 v[24:27], v[24:25], off
	v_lshl_add_u64 v[84:85], v[84:85], 0, s[14:15]
	global_load_dwordx4 v[28:31], v[28:29], off
	s_nop 0
	global_load_dwordx4 v[108:111], v[112:113], off offset:16
	s_nop 0
	global_load_dwordx4 v[112:115], v[112:113], off
	s_nop 0
	global_load_dwordx4 v[116:119], v[120:121], off offset:16
	s_nop 0
	global_load_dwordx4 v[120:123], v[120:121], off
	ds_read_b64 v[124:125], v158
	v_lshl_add_u64 v[86:87], v[86:87], 0, s[14:15]
	v_lshl_add_u64 v[88:89], v[88:89], 0, s[14:15]
	s_waitcnt vmcnt(11)
	v_lshlrev_b32_e32 v79, 16, v0
	v_and_b32_e32 v0, 0xffff0000, v0
	s_waitcnt lgkmcnt(0)
	v_sub_f32_e32 v0, v0, v124
	v_sub_f32_e32 v79, v79, v124
	v_mul_f32_e32 v0, v125, v0
	v_mul_f32_e32 v79, v125, v79
	s_waitcnt vmcnt(0)
	v_fma_f32 v0, v113, v0, v121
	v_fma_f32 v79, v112, v79, v120
	v_cvt_pk_bf16_f32 v0, v79, v0
	ds_write_b32 v159, v0 offset:1024
	v_lshlrev_b32_e32 v0, 16, v1
	v_sub_f32_e32 v0, v0, v124
	v_and_b32_e32 v1, 0xffff0000, v1
	v_mul_f32_e32 v0, v125, v0
	v_sub_f32_e32 v1, v1, v124
	v_fma_f32 v0, v114, v0, v122
	v_mul_f32_e32 v1, v125, v1
	v_fma_f32 v1, v115, v1, v123
	v_cvt_pk_bf16_f32 v0, v0, v1
	ds_write_b32 v159, v0 offset:1028
	v_lshlrev_b32_e32 v0, 16, v2
	v_sub_f32_e32 v0, v0, v124
	v_and_b32_e32 v1, 0xffff0000, v2
	v_mul_f32_e32 v0, v125, v0
	v_sub_f32_e32 v1, v1, v124
	v_fma_f32 v0, v108, v0, v116
	v_mul_f32_e32 v1, v125, v1
	v_fma_f32 v1, v109, v1, v117
	v_cvt_pk_bf16_f32 v0, v0, v1
	ds_write_b32 v159, v0 offset:1032
	v_lshlrev_b32_e32 v0, 16, v3
	v_sub_f32_e32 v0, v0, v124
	v_and_b32_e32 v1, 0xffff0000, v3
	v_mul_f32_e32 v0, v125, v0
	v_sub_f32_e32 v1, v1, v124
	v_fma_f32 v0, v110, v0, v118
	v_mul_f32_e32 v1, v125, v1
	v_fma_f32 v1, v111, v1, v119
	v_cvt_pk_bf16_f32 v0, v0, v1
	ds_write_b32 v159, v0 offset:1036
	ds_write_b128 v160, v[4:7] offset:34304
	ds_read_b64 v[0:1], v161
	v_lshlrev_b32_e32 v2, 16, v8
	v_and_b32_e32 v3, 0xffff0000, v8
	s_waitcnt lgkmcnt(0)
	v_sub_f32_e32 v2, v2, v0
	v_mul_f32_e32 v2, v1, v2
	v_sub_f32_e32 v3, v3, v0
	v_fma_f32 v2, v112, v2, v120
	v_mul_f32_e32 v3, v1, v3
	v_fma_f32 v3, v113, v3, v121
	v_cvt_pk_bf16_f32 v2, v2, v3
	ds_write_b32 v180, v2 offset:1024
	v_lshlrev_b32_e32 v2, 16, v9
	v_sub_f32_e32 v2, v2, v0
	v_and_b32_e32 v3, 0xffff0000, v9
	v_mul_f32_e32 v2, v1, v2
	v_sub_f32_e32 v3, v3, v0
	v_fma_f32 v2, v114, v2, v122
	v_mul_f32_e32 v3, v1, v3
	v_fma_f32 v3, v115, v3, v123
	v_cvt_pk_bf16_f32 v2, v2, v3
	ds_write_b32 v180, v2 offset:1028
	v_lshlrev_b32_e32 v2, 16, v10
	v_sub_f32_e32 v2, v2, v0
	v_and_b32_e32 v3, 0xffff0000, v10
	v_mul_f32_e32 v2, v1, v2
	v_sub_f32_e32 v3, v3, v0
	v_fma_f32 v2, v108, v2, v116
	v_mul_f32_e32 v3, v1, v3
	v_fma_f32 v3, v109, v3, v117
	v_cvt_pk_bf16_f32 v2, v2, v3
	ds_write_b32 v180, v2 offset:1032
	v_lshlrev_b32_e32 v2, 16, v11
	v_and_b32_e32 v3, 0xffff0000, v11
	v_sub_f32_e32 v2, v2, v0
	v_sub_f32_e32 v0, v3, v0
	v_mul_f32_e32 v0, v1, v0
	v_mul_f32_e32 v2, v1, v2
	v_fma_f32 v0, v111, v0, v119
	v_fma_f32 v2, v110, v2, v118
	v_cvt_pk_bf16_f32 v0, v2, v0
	ds_write_b32 v180, v0 offset:1036
	ds_write_b128 v181, v[12:15] offset:34304
	ds_read_b64 v[0:1], v182
	v_lshlrev_b32_e32 v2, 16, v16
	v_and_b32_e32 v3, 0xffff0000, v16
	s_waitcnt lgkmcnt(0)
	v_sub_f32_e32 v2, v2, v0
	v_mul_f32_e32 v2, v1, v2
	v_sub_f32_e32 v3, v3, v0
	v_fma_f32 v2, v112, v2, v120
	v_mul_f32_e32 v3, v1, v3
	v_fma_f32 v3, v113, v3, v121
	v_cvt_pk_bf16_f32 v2, v2, v3
	ds_write_b32 v183, v2 offset:1024
	v_lshlrev_b32_e32 v2, 16, v17
	v_sub_f32_e32 v2, v2, v0
	v_and_b32_e32 v3, 0xffff0000, v17
	v_mul_f32_e32 v2, v1, v2
	v_sub_f32_e32 v3, v3, v0
	v_fma_f32 v2, v114, v2, v122
	v_mul_f32_e32 v3, v1, v3
	v_fma_f32 v3, v115, v3, v123
	v_cvt_pk_bf16_f32 v2, v2, v3
	ds_write_b32 v183, v2 offset:1028
	v_lshlrev_b32_e32 v2, 16, v18
	v_sub_f32_e32 v2, v2, v0
	v_and_b32_e32 v3, 0xffff0000, v18
	v_mul_f32_e32 v2, v1, v2
	v_sub_f32_e32 v3, v3, v0
	v_fma_f32 v2, v108, v2, v116
	v_mul_f32_e32 v3, v1, v3
	v_fma_f32 v3, v109, v3, v117
	v_cvt_pk_bf16_f32 v2, v2, v3
	ds_write_b32 v183, v2 offset:1032
	v_lshlrev_b32_e32 v2, 16, v19
	v_and_b32_e32 v3, 0xffff0000, v19
	v_sub_f32_e32 v2, v2, v0
	v_sub_f32_e32 v0, v3, v0
	v_mul_f32_e32 v0, v1, v0
	v_mul_f32_e32 v2, v1, v2
	v_fma_f32 v0, v111, v0, v119
	v_fma_f32 v2, v110, v2, v118
	v_cvt_pk_bf16_f32 v0, v2, v0
	ds_write_b32 v183, v0 offset:1036
	ds_write_b128 v184, v[20:23] offset:34304
	ds_read_b64 v[0:1], v185
	v_lshlrev_b32_e32 v2, 16, v24
	v_and_b32_e32 v3, 0xffff0000, v24
	s_waitcnt lgkmcnt(0)
	v_sub_f32_e32 v2, v2, v0
	v_mul_f32_e32 v2, v1, v2
	v_sub_f32_e32 v3, v3, v0
	v_fma_f32 v2, v112, v2, v120
	v_mul_f32_e32 v3, v1, v3
	v_fma_f32 v3, v113, v3, v121
	v_cvt_pk_bf16_f32 v2, v2, v3
	ds_write_b32 v186, v2 offset:1024
	v_lshlrev_b32_e32 v2, 16, v25
	v_sub_f32_e32 v2, v2, v0
	v_and_b32_e32 v3, 0xffff0000, v25
	v_mul_f32_e32 v2, v1, v2
	v_sub_f32_e32 v3, v3, v0
	v_fma_f32 v2, v114, v2, v122
	v_mul_f32_e32 v3, v1, v3
	v_fmac_f32_e32 v123, v115, v3
	v_cvt_pk_bf16_f32 v2, v2, v123
	ds_write_b32 v186, v2 offset:1028
	v_lshlrev_b32_e32 v2, 16, v26
	v_sub_f32_e32 v2, v2, v0
	v_and_b32_e32 v3, 0xffff0000, v26
	v_mul_f32_e32 v2, v1, v2
	v_sub_f32_e32 v3, v3, v0
	v_fma_f32 v2, v108, v2, v116
	v_mul_f32_e32 v3, v1, v3
	v_fma_f32 v3, v109, v3, v117
	v_cvt_pk_bf16_f32 v2, v2, v3
	ds_write_b32 v186, v2 offset:1032
	v_lshlrev_b32_e32 v2, 16, v27
	v_and_b32_e32 v3, 0xffff0000, v27
	v_sub_f32_e32 v2, v2, v0
	v_sub_f32_e32 v0, v3, v0
	v_mul_f32_e32 v2, v1, v2
	v_mul_f32_e32 v0, v1, v0
	v_fma_f32 v2, v110, v2, v118
	v_fmac_f32_e32 v119, v111, v0
	v_cvt_pk_bf16_f32 v0, v2, v119
	ds_write_b32 v186, v0 offset:1036
	ds_write_b128 v187, v[28:31] offset:34304
	v_lshl_add_u64 v[0:1], s[22:23], 0, v[98:99]
	s_waitcnt lgkmcnt(0)
	s_barrier
; __device__ void ph_gmlp(const bf16_t* __restrict__ PROJ, bf16_t* __restrict__ GA, const bf16_t* __restrict__ GWS  ,
;                         const float* __restrict__ lng, const float* __restrict__ lnb, const float* __restrict__ bs  , unsigned char* smem) {
;     ...
;             const int n = lane & 15, kg = lane >> 4, d0 = wave * 16;
;             u32x2 uu[8];
; #pragma unroll
;             for (int qt = 0; qt < 8; ++qt) uu[qt] = *(const u32x2*)(PROJ + (size_t)(tok0 + qt * 16 + n) * 8192 + g * 128 + d0 + 4 * kg);
;             const unsigned short* vts = (const unsigned short*)vt;
; #pragma unroll
;             for (int ks = 0; ks < 4; ++ks) {
;                 bf16x8 vf;
; #pragma unroll
;                 for (int j = 0; j < 8; ++j) vf[j] = (short)vts[(ks * 32 + kg * 8 + j) * 130 + d0 + n];
; #pragma unroll
;                 for (int qt = 0; qt < 8; ++qt) {
;                     const bf16x8 wf = *(const bf16x8*)(wsl + (qt * 16 + n) * 136 + ks * 32 + kg * 8);
;                     acc[qt] = __builtin_amdgcn_mfma_f32_16x16x32_bf16(vf, wf, acc[qt], 0, 0, 0); } }
; #pragma unroll
;             for (int qt = 0; qt < 8; ++qt) { const int q = qt * 16 + n, dd = g * 128 + d0 + 4 * kg; const size_t tok = (size_t)(tok0 + q);
;                 const float bq = bs[g * 128 + q];
	global_load_dwordx2 v[124:125], v[0:1], off
	v_lshl_add_u64 v[0:1], s[22:23], 0, v[100:101]
	global_load_dwordx2 v[122:123], v[0:1], off
	v_lshl_add_u64 v[0:1], s[22:23], 0, v[102:103]
	global_load_dwordx2 v[120:121], v[0:1], off
	v_lshl_add_u64 v[0:1], s[22:23], 0, v[104:105]
	global_load_dwordx2 v[118:119], v[0:1], off
	v_lshl_add_u64 v[0:1], s[22:23], 0, v[106:107]
	global_load_dwordx2 v[116:117], v[0:1], off
	v_lshl_add_u64 v[0:1], s[22:23], 0, v[94:95]
	global_load_dwordx2 v[114:115], v[0:1], off
	v_lshl_add_u64 v[0:1], s[22:23], 0, v[90:91]
	global_load_dwordx2 v[110:111], v[0:1], off
	v_lshl_add_u64 v[0:1], s[22:23], 0, v[76:77]
	global_load_dwordx2 v[108:109], v[0:1], off
	v_lshl_add_u64 v[214:215], v[80:81], 0, s[26:27]
	global_load_dword v206, v[214:215], off
	global_load_dword v207, v[214:215], off offset:64
	global_load_dword v208, v[214:215], off offset:128
	global_load_dword v209, v[214:215], off offset:192
	global_load_dword v210, v[214:215], off offset:256
	global_load_dword v211, v[214:215], off offset:320
	global_load_dword v212, v[214:215], off offset:384
	global_load_dword v213, v[214:215], off offset:448
	ds_read_u16 v0, v188 offset:1024
	ds_read_u16 v4, v188 offset:1284
	ds_read_u16 v1, v188 offset:1544
	ds_read_u16 v5, v188 offset:1804
	ds_read_u16 v2, v188 offset:2064
	ds_read_u16 v6, v188 offset:2324
	ds_read_u16 v3, v188 offset:2584
	ds_read_u16 v7, v188 offset:2844
	s_waitcnt lgkmcnt(4)
	v_perm_b32 v1, v5, v1, s2
	v_perm_b32 v0, v4, v0, s2
	s_waitcnt lgkmcnt(2)
	v_perm_b32 v2, v6, v2, s2
	ds_read_b128 v[8:11], v189 offset:38656
	s_waitcnt lgkmcnt(1)
	v_perm_b32 v3, v7, v3, s2
	ds_read_b128 v[4:7], v189 offset:34304
	ds_read_b128 v[12:15], v189 offset:43008
	ds_read_b128 v[16:19], v189 offset:47360
	ds_read_b128 v[20:23], v189 offset:51712
	ds_read_b128 v[24:27], v189 offset:56064
	ds_read_b128 v[28:31], v189 offset:60416
	ds_read_b128 v[190:193], v189 offset:64768
	s_waitcnt lgkmcnt(6)
	v_mfma_f32_16x16x32_bf16 v[4:7], v[0:3], v[4:7], 0
	v_lshl_add_u64 v[76:77], v[76:77], 0, s[14:15]
	v_lshl_add_u64 v[90:91], v[90:91], 0, s[14:15]
	v_lshl_add_u64 v[94:95], v[94:95], 0, s[14:15]
	v_mfma_f32_16x16x32_bf16 v[8:11], v[0:3], v[8:11], 0
	v_lshl_add_u64 v[98:99], v[98:99], 0, s[14:15]
	v_lshl_add_u64 v[100:101], v[100:101], 0, s[14:15]
	v_lshl_add_u64 v[102:103], v[102:103], 0, s[14:15]
	s_waitcnt lgkmcnt(5)
	v_mfma_f32_16x16x32_bf16 v[12:15], v[0:3], v[12:15], 0
	v_lshl_add_u64 v[104:105], v[104:105], 0, s[14:15]
	v_lshl_add_u64 v[106:107], v[106:107], 0, s[14:15]
	s_waitcnt lgkmcnt(4)
	v_mfma_f32_16x16x32_bf16 v[16:19], v[0:3], v[16:19], 0
	s_waitcnt lgkmcnt(3)
	v_mfma_f32_16x16x32_bf16 v[20:23], v[0:3], v[20:23], 0
	s_waitcnt lgkmcnt(2)
	v_mfma_f32_16x16x32_bf16 v[24:27], v[0:3], v[24:27], 0
	s_waitcnt lgkmcnt(1)
	v_mfma_f32_16x16x32_bf16 v[28:31], v[0:3], v[28:31], 0
	s_waitcnt lgkmcnt(0)
	v_mfma_f32_16x16x32_bf16 v[0:3], v[0:3], v[190:193], 0
	ds_read_u16 v79, v188 offset:9344
	ds_read_u16 v112, v188 offset:9604
	ds_read_u16 v113, v188 offset:9864
	ds_read_u16 v126, v188 offset:10124
	ds_read_u16 v127, v188 offset:10384
	ds_read_u16 v128, v188 offset:10644
	ds_read_u16 v190, v188 offset:10904
	ds_read_u16 v191, v188 offset:11164
	ds_read_b128 v[194:197], v189 offset:34368
	s_waitcnt lgkmcnt(3)
	v_perm_b32 v192, v128, v127, s2
	s_waitcnt lgkmcnt(1)
	v_perm_b32 v193, v191, v190, s2
	v_perm_b32 v191, v126, v113, s2
	v_perm_b32 v190, v112, v79, s2
	s_waitcnt lgkmcnt(0)
	s_nop 0
	v_mfma_f32_16x16x32_bf16 v[4:7], v[190:193], v[194:197], v[4:7]
	ds_read_b128 v[194:197], v189 offset:38720
	s_waitcnt lgkmcnt(0)
	v_mfma_f32_16x16x32_bf16 v[8:11], v[190:193], v[194:197], v[8:11]
	ds_read_b128 v[194:197], v189 offset:43072
	s_waitcnt lgkmcnt(0)
	v_mfma_f32_16x16x32_bf16 v[12:15], v[190:193], v[194:197], v[12:15]
	ds_read_b128 v[194:197], v189 offset:47424
	s_waitcnt lgkmcnt(0)
	v_mfma_f32_16x16x32_bf16 v[16:19], v[190:193], v[194:197], v[16:19]
	ds_read_b128 v[194:197], v189 offset:51776
	s_waitcnt lgkmcnt(0)
	v_mfma_f32_16x16x32_bf16 v[20:23], v[190:193], v[194:197], v[20:23]
	ds_read_b128 v[194:197], v189 offset:56128
	s_waitcnt lgkmcnt(0)
	v_mfma_f32_16x16x32_bf16 v[24:27], v[190:193], v[194:197], v[24:27]
	ds_read_b128 v[194:197], v189 offset:60480
	s_waitcnt lgkmcnt(0)
	v_mfma_f32_16x16x32_bf16 v[28:31], v[190:193], v[194:197], v[28:31]
	ds_read_b128 v[194:197], v189 offset:64832
	s_waitcnt lgkmcnt(0)
	v_mfma_f32_16x16x32_bf16 v[0:3], v[190:193], v[194:197], v[0:3]
	ds_read_u16 v79, v188 offset:17664
	ds_read_u16 v112, v188 offset:17924
	ds_read_u16 v113, v188 offset:18184
	ds_read_u16 v126, v188 offset:18444
	ds_read_u16 v127, v188 offset:18704
	ds_read_u16 v128, v188 offset:18964
	ds_read_u16 v190, v188 offset:19224
	ds_read_u16 v191, v188 offset:19484
	ds_read_b128 v[194:197], v189 offset:34432
	s_waitcnt lgkmcnt(3)
	v_perm_b32 v192, v128, v127, s2
	s_waitcnt vmcnt(15)
	v_lshlrev_b32_e32 v128, 16, v124
	s_waitcnt lgkmcnt(1)
	v_perm_b32 v193, v191, v190, s2
	v_perm_b32 v191, v126, v113, s2
	v_perm_b32 v190, v112, v79, s2
	v_ashrrev_i32_e32 v79, 31, v78
	v_lshl_add_u64 v[126:127], v[80:81], 0, s[26:27]
	s_waitcnt lgkmcnt(0)
	v_mfma_f32_16x16x32_bf16 v[4:7], v[190:193], v[194:197], v[4:7]
	ds_read_b128 v[194:197], v189 offset:38784
	v_lshl_add_u64 v[112:113], v[78:79], 1, s[6:7]
	v_and_b32_e32 v124, 0xffff0000, v124
	s_waitcnt lgkmcnt(0)
	v_mfma_f32_16x16x32_bf16 v[8:11], v[190:193], v[194:197], v[8:11]
	ds_read_b128 v[194:197], v189 offset:43136
	s_add_u32 s26, s26, 0x200
	s_addc_u32 s27, s27, 0
	s_waitcnt lgkmcnt(0)
	v_mfma_f32_16x16x32_bf16 v[12:15], v[190:193], v[194:197], v[12:15]
	ds_read_b128 v[194:197], v189 offset:47488
	v_add_u32_e32 v78, 0x80, v78
	s_cmpk_eq_i32 s26, 0xc00
	s_waitcnt lgkmcnt(0)
; __device__ __forceinline__ unsigned cvt_pk_bf16(float lo, float hi) { unsigned r; asm volatile("v_cvt_pk_bf16_f32 %0, %1, %2" : "=v"(r) : "v"(lo), "v"(hi)); return r; }
; __device__ __forceinline__ float bflo(unsigned w) { return __uint_as_float(w << 16); }
; __device__ __forceinline__ float bfhi(unsigned w) { return __uint_as_float(w & 0xffff0000u); }
; __device__ void ph_gmlp(const bf16_t* __restrict__ PROJ, bf16_t* __restrict__ GA, const bf16_t* __restrict__ GWS  ,
;                         const float* __restrict__ lng, const float* __restrict__ lnb, const float* __restrict__ bs  , unsigned char* smem) {
;     ...
;                 for (int qt = 0; qt < 8; ++qt) {
;                     const bf16x8 wf = *(const bf16x8*)(wsl + (qt * 16 + n) * 136 + ks * 32 + kg * 8);
;                     acc[qt] = __builtin_amdgcn_mfma_f32_16x16x32_bf16(vf, wf, acc[qt], 0, 0, 0); } }
; #pragma unroll
;             for (int qt = 0; qt < 8; ++qt) { const int q = qt * 16 + n, dd = g * 128 + d0 + 4 * kg; const size_t tok = (size_t)(tok0 + q);
;                 const float bq = bs[g * 128 + q];
;                 u32x2 o; o.x = cvt_pk_bf16(bflo(uu[qt].x) * (acc[qt][0] + bq), bfhi(uu[qt].x) * (acc[qt][1] + bq)); o.y = cvt_pk_bf16(bflo(uu[qt].y) * (acc[qt][2] + bq), bfhi(uu[qt].y) * (acc[qt][3] + bq));
;                 *(u32x2*)(GA + tok * 1536 + dd) = o; }
	v_mfma_f32_16x16x32_bf16 v[16:19], v[190:193], v[194:197], v[16:19]
	ds_read_b128 v[194:197], v189 offset:51840
	s_waitcnt lgkmcnt(0)
	v_mfma_f32_16x16x32_bf16 v[194:197], v[190:193], v[194:197], v[20:23]
	s_nop 2
	ds_read_b128 v[20:23], v189 offset:56192
	s_waitcnt lgkmcnt(0)
	v_mfma_f32_16x16x32_bf16 v[198:201], v[190:193], v[20:23], v[24:27]
	ds_read_b128 v[20:23], v189 offset:60544
	s_waitcnt lgkmcnt(0)
	v_mfma_f32_16x16x32_bf16 v[202:205], v[190:193], v[20:23], v[28:31]
	ds_read_b128 v[20:23], v189 offset:64896
	s_waitcnt lgkmcnt(0)
	v_mfma_f32_16x16x32_bf16 v[0:3], v[190:193], v[20:23], v[0:3]
	ds_read_u16 v20, v188 offset:25984
	ds_read_u16 v21, v188 offset:26244
	ds_read_u16 v22, v188 offset:26504
	ds_read_u16 v23, v188 offset:26764
	ds_read_u16 v24, v188 offset:27024
	ds_read_u16 v25, v188 offset:27284
	ds_read_u16 v26, v188 offset:27544
	ds_read_u16 v27, v188 offset:27804
	s_waitcnt lgkmcnt(4)
	v_perm_b32 v191, v23, v22, s2
	s_waitcnt lgkmcnt(2)
	v_perm_b32 v192, v25, v24, s2
	v_perm_b32 v190, v21, v20, s2
	s_waitcnt lgkmcnt(0)
	v_perm_b32 v193, v27, v26, s2
	ds_read_b128 v[20:23], v189 offset:34496
	s_waitcnt lgkmcnt(0)
	v_mfma_f32_16x16x32_bf16 v[28:31], v[190:193], v[20:23], v[4:7]
	s_nop 2
	ds_read_b128 v[4:7], v189 offset:38848
	s_waitcnt lgkmcnt(0)
	v_mfma_f32_16x16x32_bf16 v[24:27], v[190:193], v[4:7], v[8:11]
	ds_read_b128 v[4:7], v189 offset:43200
	s_waitcnt vmcnt(7)
	v_add_f32_e32 v28, v28, v206
	s_waitcnt lgkmcnt(0)
	v_mfma_f32_16x16x32_bf16 v[20:23], v[190:193], v[4:7], v[12:15]
	ds_read_b128 v[4:7], v189 offset:47552
	v_add_f32_e32 v29, v29, v206
	v_mul_f32_e32 v28, v28, v128
	s_waitcnt lgkmcnt(0)
	v_mfma_f32_16x16x32_bf16 v[16:19], v[190:193], v[4:7], v[16:19]
	ds_read_b128 v[4:7], v189 offset:51904
	v_mul_f32_e32 v29, v29, v124
	v_add_f32_e32 v30, v30, v206
	s_waitcnt lgkmcnt(0)
	v_mfma_f32_16x16x32_bf16 v[12:15], v[190:193], v[4:7], v[194:197]
	ds_read_b128 v[4:7], v189 offset:56256
	s_nop 1
	ds_read_b128 v[194:197], v189 offset:64960
	v_add_f32_e32 v31, v31, v206
	s_waitcnt lgkmcnt(1)
	v_mfma_f32_16x16x32_bf16 v[8:11], v[190:193], v[4:7], v[198:201]
	ds_read_b128 v[4:7], v189 offset:60608
	v_cvt_pk_bf16_f32 v28, v28, v29
	v_lshlrev_b32_e32 v29, 16, v125
	v_mul_f32_e32 v29, v30, v29
	v_and_b32_e32 v30, 0xffff0000, v125
	v_mul_f32_e32 v30, v31, v30
	v_cvt_pk_bf16_f32 v29, v29, v30
	v_lshl_add_u64 v[30:31], v[112:113], 0, v[32:33]
	global_store_dwordx2 v[30:31], v[28:29], off
	v_lshlrev_b32_e32 v29, 16, v122
	s_waitcnt lgkmcnt(0)
	v_mfma_f32_16x16x32_bf16 v[4:7], v[190:193], v[4:7], v[202:205]
	s_waitcnt vmcnt(7)
	v_add_f32_e32 v24, v24, v207
	v_mul_f32_e32 v24, v24, v29
	v_and_b32_e32 v29, 0xffff0000, v122
	v_add_f32_e32 v25, v25, v207
	v_mul_f32_e32 v25, v25, v29
	v_cvt_pk_bf16_f32 v24, v24, v25
	v_lshlrev_b32_e32 v25, 16, v123
	v_add_f32_e32 v26, v26, v207
	v_mul_f32_e32 v25, v26, v25
	v_and_b32_e32 v26, 0xffff0000, v123
	v_add_f32_e32 v27, v27, v207
	v_mul_f32_e32 v26, v27, v26
	v_cvt_pk_bf16_f32 v25, v25, v26
	v_lshl_add_u64 v[26:27], v[112:113], 0, v[34:35]
	global_store_dwordx2 v[26:27], v[24:25], off
	v_lshlrev_b32_e32 v25, 16, v120
	v_mfma_f32_16x16x32_bf16 v[0:3], v[190:193], v[194:197], v[0:3]
	s_waitcnt vmcnt(7)
	v_add_f32_e32 v20, v20, v208
	v_mul_f32_e32 v20, v20, v25
	v_and_b32_e32 v25, 0xffff0000, v120
	v_add_f32_e32 v21, v21, v208
	v_mul_f32_e32 v21, v21, v25
	v_cvt_pk_bf16_f32 v20, v20, v21
	v_lshlrev_b32_e32 v21, 16, v121
	v_add_f32_e32 v22, v22, v208
	v_mul_f32_e32 v21, v22, v21
	v_and_b32_e32 v22, 0xffff0000, v121
	v_add_f32_e32 v23, v23, v208
	v_mul_f32_e32 v22, v23, v22
	v_cvt_pk_bf16_f32 v21, v21, v22
	v_lshl_add_u64 v[22:23], v[112:113], 0, v[36:37]
	global_store_dwordx2 v[22:23], v[20:21], off
	v_lshlrev_b32_e32 v21, 16, v118
	s_waitcnt vmcnt(7)
	v_add_f32_e32 v16, v16, v209
	v_mul_f32_e32 v16, v16, v21
	v_and_b32_e32 v21, 0xffff0000, v118
	v_add_f32_e32 v17, v17, v209
	v_mul_f32_e32 v17, v17, v21
	v_cvt_pk_bf16_f32 v16, v16, v17
	v_lshlrev_b32_e32 v17, 16, v119
	v_add_f32_e32 v18, v18, v209
	v_mul_f32_e32 v17, v18, v17
	v_and_b32_e32 v18, 0xffff0000, v119
	v_add_f32_e32 v19, v19, v209
	v_mul_f32_e32 v18, v19, v18
	v_cvt_pk_bf16_f32 v17, v17, v18
	v_lshl_add_u64 v[18:19], v[112:113], 0, v[38:39]
	global_store_dwordx2 v[18:19], v[16:17], off
	v_lshlrev_b32_e32 v17, 16, v116
	s_waitcnt vmcnt(7)
	v_add_f32_e32 v12, v12, v210
	v_mul_f32_e32 v12, v12, v17
	v_and_b32_e32 v17, 0xffff0000, v116
	v_add_f32_e32 v13, v13, v210
	v_mul_f32_e32 v13, v13, v17
	v_cvt_pk_bf16_f32 v12, v12, v13
	v_lshlrev_b32_e32 v13, 16, v117
	v_add_f32_e32 v14, v14, v210
	v_mul_f32_e32 v13, v14, v13
	v_and_b32_e32 v14, 0xffff0000, v117
	v_add_f32_e32 v15, v15, v210
	v_mul_f32_e32 v14, v15, v14
	v_cvt_pk_bf16_f32 v13, v13, v14
	v_lshl_add_u64 v[14:15], v[112:113], 0, v[40:41]
	global_store_dwordx2 v[14:15], v[12:13], off
	v_lshlrev_b32_e32 v13, 16, v114
	s_waitcnt vmcnt(7)
	v_add_f32_e32 v8, v8, v211
	v_mul_f32_e32 v8, v8, v13
	v_and_b32_e32 v13, 0xffff0000, v114
	v_add_f32_e32 v9, v9, v211
	v_mul_f32_e32 v9, v9, v13
	v_cvt_pk_bf16_f32 v8, v8, v9
	v_lshlrev_b32_e32 v9, 16, v115
	v_add_f32_e32 v10, v10, v211
	v_mul_f32_e32 v9, v10, v9
	v_and_b32_e32 v10, 0xffff0000, v115
	v_add_f32_e32 v11, v11, v211
	v_mul_f32_e32 v10, v11, v10
	v_cvt_pk_bf16_f32 v9, v9, v10
	v_lshl_add_u64 v[10:11], v[112:113], 0, v[42:43]
	global_store_dwordx2 v[10:11], v[8:9], off
	v_lshlrev_b32_e32 v9, 16, v110
	s_waitcnt vmcnt(7)
	v_add_f32_e32 v4, v4, v212
	v_mul_f32_e32 v4, v4, v9
	v_and_b32_e32 v9, 0xffff0000, v110
	v_add_f32_e32 v5, v5, v212
	v_mul_f32_e32 v5, v5, v9
	v_cvt_pk_bf16_f32 v4, v4, v5
	v_lshlrev_b32_e32 v5, 16, v111
	v_add_f32_e32 v6, v6, v212
	v_mul_f32_e32 v5, v6, v5
	v_and_b32_e32 v6, 0xffff0000, v111
	v_add_f32_e32 v7, v7, v212
	v_mul_f32_e32 v6, v7, v6
	v_cvt_pk_bf16_f32 v5, v5, v6
	v_lshl_add_u64 v[6:7], v[112:113], 0, v[64:65]
	global_store_dwordx2 v[6:7], v[4:5], off
	v_lshlrev_b32_e32 v5, 16, v108
	s_waitcnt vmcnt(7)
	v_add_f32_e32 v0, v0, v213
	v_mul_f32_e32 v0, v0, v5
	v_and_b32_e32 v5, 0xffff0000, v108
	v_add_f32_e32 v1, v1, v213
	v_mul_f32_e32 v1, v1, v5
	v_cvt_pk_bf16_f32 v0, v0, v1
	v_lshlrev_b32_e32 v1, 16, v109
	v_add_f32_e32 v2, v2, v213
	v_mul_f32_e32 v1, v2, v1
	v_and_b32_e32 v2, 0xffff0000, v109
	v_add_f32_e32 v3, v3, v213
	v_mul_f32_e32 v2, v3, v2
	v_cvt_pk_bf16_f32 v1, v1, v2
	v_lshl_add_u64 v[2:3], v[112:113], 0, v[66:67]
	global_store_dwordx2 v[2:3], v[0:1], off
	s_barrier
	s_cbranch_scc0 .LBB0_724
	s_add_i32 s39, s39, s34
	s_add_i32 s38, s38, s17
	s_cmpk_gt_i32 s39, 0xff
	s_cbranch_scc0 .LBB0_713
